# c24 but DIFF per-step barrier moved from step end to just before the last PV MFMA group (MFMA-first segment head after barrier release)
# baseline (speedup 1.0000x reference)
.LBB0_1422:
	s_lshl_b32 s18, s44, 14
	s_add_i32 s52, s81, s18
	s_mov_b32 m0, s52
	v_lshl_add_u64 v[0:1], v[194:195], 0, s[14:15]
	global_load_lds_dwordx4 v[194:195], off
	s_add_i32 m0, s52, 0x2000
	s_mul_i32 s52, s54, 0x2100
	s_add_i32 s52, s22, s52
	global_load_lds_dwordx4 v[0:1], off
	s_add_i32 m0, s52, 0xc000
	s_add_i32 s52, s45, -1
	s_cmp_lt_u32 s52, s2
	s_cselect_b32 s55, s52, s3
	s_lshl_b32 s56, s55, 6
	v_mad_u64_u32 v[0:1], s[52:53], s56, v209, v[192:193]
	v_lshl_add_u64 v[0:1], v[0:1], 0, s[10:11]
	global_load_lds_dwordx4 v[0:1], off
	s_mul_i32 s52, s55, 0x60000
	s_mul_hi_u32 s53, s56, 0x1800
	s_mul_i32 s55, s69, 0x2100
	s_add_i32 s71, s55, 0
	s_sub_i32 s55, s65, 64
	v_cvt_f32_u32_e32 v0, s55
	v_add_u32_e32 v166, s71, v220
	v_add_u32_e32 v167, s71, v217
	ds_read_b128 v[4:7], v166 offset:49152
	ds_read_b128 v[8:11], v167 offset:49152
	v_sub_f32_e32 v196, v0, v161
	v_fma_f32 v0, v210, v196, -v221
	v_cvt_pk_bf16_f32 v1, v0, v3
	v_lshlrev_b32_e32 v1, 16, v1
	v_sub_f32_e32 v0, v0, v1
	v_cvt_pk_bf16_f32 v2, v0, v3
	v_lshlrev_b32_e32 v2, 16, v2
	v_sub_f32_e32 v0, v0, v2
	v_cvt_pk_bf16_f32 v1, v1, v2
	v_cvt_pk_bf16_f32 v0, v0, v3
	s_nop 0
	v_cndmask_b32_e64 v2, 0, v0, s[4:5]
	v_cndmask_b32_e64 v0, 0, v160, s[4:5]
	v_cndmask_b32_e64 v1, 0, v1, s[4:5]
	s_nop 1
	v_mfma_f32_32x32x16_bf16 v[128:143], v[248:251], v[0:3], 0
	v_add_f32_e32 v226, v96, v97
	v_add_f32_e32 v226, v98, v226
	v_add_f32_e32 v226, v99, v226
	v_add_f32_e32 v226, v100, v226
	v_mfma_f32_32x32x16_bf16 v[112:127], v[252:255], v[0:3], 0
	v_add_f32_e32 v1, v101, v226
	v_add_f32_e32 v1, v102, v1
	s_waitcnt lgkmcnt(0)
	v_mfma_f32_32x32x16_bf16 v[128:143], v[8:11], v[156:159], v[128:143]
	v_add_f32_e32 v1, v103, v1
	v_add_f32_e32 v1, v104, v1
	v_add_f32_e32 v1, v105, v1
	v_add_f32_e32 v1, v106, v1
	v_add_f32_e32 v1, v107, v1
	v_add_f32_e32 v1, v108, v1
	v_add_f32_e32 v1, v109, v1
	v_mfma_f32_32x32x16_bf16 v[112:127], v[4:7], v[156:159], v[112:127]
	ds_read_b128 v[4:7], v166 offset:51264
	ds_read_b128 v[8:11], v167 offset:51264
	v_add_f32_e32 v1, v110, v1
	v_add_f32_e32 v1, v111, v1
	v_add_f32_e32 v1, v80, v1
	v_add_f32_e32 v1, v81, v1
	v_add_f32_e32 v1, v82, v1
	v_add_f32_e32 v1, v83, v1
	s_waitcnt lgkmcnt(0)
	v_mfma_f32_32x32x16_bf16 v[128:143], v[8:11], v[152:155], v[128:143]
	v_add_f32_e32 v1, v84, v1
	v_add_f32_e32 v1, v85, v1
	v_add_f32_e32 v1, v86, v1
	v_add_f32_e32 v1, v87, v1
	v_add_f32_e32 v1, v88, v1
	v_add_f32_e32 v1, v89, v1
	v_add_f32_e32 v1, v90, v1
	v_mfma_f32_32x32x16_bf16 v[112:127], v[4:7], v[152:155], v[112:127]
	ds_read_b128 v[4:7], v166 offset:53376
	ds_read_b128 v[8:11], v167 offset:53376
	v_add_f32_e32 v1, v91, v1
	v_add_f32_e32 v1, v92, v1
	v_add_f32_e32 v1, v93, v1
	v_add_f32_e32 v1, v94, v1
	v_add_f32_e32 v223, v95, v1
	v_mov_b32_e32 v224, v223
	s_waitcnt lgkmcnt(0)
	v_mfma_f32_32x32x16_bf16 v[128:143], v[8:11], v[148:151], v[128:143]
	v_permlane32_swap_b32_e32 v223, v224
	v_mfma_f32_32x32x16_bf16 v[112:127], v[4:7], v[148:151], v[112:127]
	ds_read_b128 v[4:7], v166 offset:55488
	ds_read_b128 v[8:11], v167 offset:55488
	v_cvt_pk_bf16_f32 v166, v96, v97
	v_cvt_pk_bf16_f32 v167, v98, v99
	v_cvt_pk_bf16_f32 v168, v100, v101
	v_cvt_pk_bf16_f32 v169, v102, v103
	v_cvt_pk_bf16_f32 v12, v104, v105
	v_cvt_pk_bf16_f32 v13, v106, v107
	s_waitcnt lgkmcnt(0)
	v_mfma_f32_32x32x16_bf16 v[128:143], v[8:11], v[144:147], v[128:143]
	v_cvt_pk_bf16_f32 v14, v108, v109
	v_cvt_pk_bf16_f32 v15, v110, v111
	v_cvt_pk_bf16_f32 v8, v80, v81
	v_cvt_pk_bf16_f32 v9, v82, v83
	v_cvt_pk_bf16_f32 v10, v84, v85
	v_cvt_pk_bf16_f32 v11, v86, v87
	v_mfma_f32_32x32x16_bf16 v[112:127], v[4:7], v[144:147], v[112:127]
	v_cvt_pk_bf16_f32 v4, v88, v89
	v_cvt_pk_bf16_f32 v5, v90, v91
	v_cvt_pk_bf16_f32 v6, v92, v93
	v_cvt_pk_bf16_f32 v7, v94, v95
	v_lshl_add_u32 v1, s54, 14, v215
	ds_read_b64_tr_b16 v[182:183], v1 offset:0
	ds_read_b64_tr_b16 v[184:185], v1 offset:0x800
	ds_read_b64_tr_b16 v[178:179], v1 offset:0x1000
	ds_read_b64_tr_b16 v[180:181], v1 offset:0x1800
	s_add_i32 s70, s45, -3
	s_add_i32 s54, s19, s45
	ds_read_b64_tr_b16 v[174:175], v1 offset:0x2000
	s_cmp_eq_u32 s54, 3
	ds_read_b64_tr_b16 v[176:177], v1 offset:0x2800
	s_cselect_b64 s[54:55], -1, 0
	ds_read_b64_tr_b16 v[170:171], v1 offset:0x3000
	v_cndmask_b32_e64 v2, 0, 1, s[54:55]
	ds_read_b64_tr_b16 v[172:173], v1 offset:0x3800
	s_cmp_lt_i32 s70, s31
	s_cbranch_scc0 .Lold_odd
	v_max3_f32 v245, v128, v129, v130
	v_max3_f32 v246, v112, v113, v114
	v_max3_f32 v245, v245, v131, v132
	v_max3_f32 v246, v246, v115, v116
	v_max3_f32 v245, v245, v133, v134
	v_max3_f32 v246, v246, v117, v118
	v_max3_f32 v245, v245, v135, v136
	v_max3_f32 v246, v246, v119, v120
	v_max3_f32 v245, v245, v137, v138
	v_max3_f32 v246, v246, v121, v122
	v_max3_f32 v245, v245, v139, v140
	v_max3_f32 v246, v246, v123, v124
	v_max3_f32 v245, v245, v141, v142
	v_max3_f32 v246, v246, v125, v126
	v_max_f32_e32 v245, v245, v143
	v_max_f32_e32 v246, v246, v127
	v_max_f32_e32 v245, v245, v246
	v_mov_b32_e32 v246, v245
	s_nop 1
	v_permlane32_swap_b32_e32 v245, v246
	v_max_f32_e32 v245, v245, v246
	v_cmp_ge_f32_e32 vcc, s68, v245
	s_cmp_eq_u64 vcc, exec
	v_mov_b32_e32 v225, 1.0
	s_cbranch_scc0 .Lf_odd_resc
.Lf_odd_exp:
	ds_read_b64_tr_b16 v[198:199], v1 offset:0x200
	ds_read_b64_tr_b16 v[200:201], v1 offset:0xa00
	ds_read_b64_tr_b16 v[230:231], v1 offset:0x1200
	ds_read_b64_tr_b16 v[232:233], v1 offset:0x1a00
	ds_read_b64_tr_b16 v[234:235], v1 offset:0x2200
	ds_read_b64_tr_b16 v[236:237], v1 offset:0x2a00
	ds_read_b64_tr_b16 v[238:239], v1 offset:0x3200
	ds_read_b64_tr_b16 v[240:241], v1 offset:0x3a00
	s_waitcnt lgkmcnt(8)
	v_mfma_f32_32x32x16_bf16 v[64:79], v[166:169], v[182:185], v[64:79]
	v_exp_f32_e32 v96, v128
	v_exp_f32_e32 v97, v129
	v_mfma_f32_32x32x16_bf16 v[64:79], v[12:15], v[178:181], v[64:79]
	v_exp_f32_e32 v98, v130
	v_exp_f32_e32 v99, v131
	v_mfma_f32_32x32x16_bf16 v[64:79], v[8:11], v[174:177], v[64:79]
	v_exp_f32_e32 v100, v132
	v_exp_f32_e32 v101, v133
	v_mfma_f32_32x32x16_bf16 v[64:79], v[4:7], v[170:173], v[64:79]
	v_exp_f32_e32 v102, v134
	v_exp_f32_e32 v103, v135
	ds_read_b64_tr_b16 v[182:183], v1 offset:0x400
	ds_read_b64_tr_b16 v[184:185], v1 offset:0xc00
	ds_read_b64_tr_b16 v[178:179], v1 offset:0x1400
	ds_read_b64_tr_b16 v[180:181], v1 offset:0x1c00
	ds_read_b64_tr_b16 v[174:175], v1 offset:0x2400
	ds_read_b64_tr_b16 v[176:177], v1 offset:0x2c00
	ds_read_b64_tr_b16 v[170:171], v1 offset:0x3400
	ds_read_b64_tr_b16 v[172:173], v1 offset:0x3c00
	s_waitcnt lgkmcnt(8)
	v_mfma_f32_32x32x16_bf16 v[48:63], v[166:169], v[198:201], v[48:63]
	v_exp_f32_e32 v104, v136
	v_exp_f32_e32 v105, v137
	v_mfma_f32_32x32x16_bf16 v[48:63], v[12:15], v[230:233], v[48:63]
	v_exp_f32_e32 v106, v138
	v_exp_f32_e32 v107, v139
	v_mfma_f32_32x32x16_bf16 v[48:63], v[8:11], v[234:237], v[48:63]
	v_exp_f32_e32 v108, v140
	v_exp_f32_e32 v109, v141
	v_mfma_f32_32x32x16_bf16 v[48:63], v[4:7], v[238:241], v[48:63]
	v_exp_f32_e32 v110, v142
	v_exp_f32_e32 v111, v143
	ds_read_b64_tr_b16 v[198:199], v1 offset:0x600
	ds_read_b64_tr_b16 v[200:201], v1 offset:0xe00
	ds_read_b64_tr_b16 v[230:231], v1 offset:0x1600
	ds_read_b64_tr_b16 v[232:233], v1 offset:0x1e00
	ds_read_b64_tr_b16 v[234:235], v1 offset:0x2600
	ds_read_b64_tr_b16 v[236:237], v1 offset:0x2e00
	ds_read_b64_tr_b16 v[238:239], v1 offset:0x3600
	ds_read_b64_tr_b16 v[240:241], v1 offset:0x3e00
	s_waitcnt lgkmcnt(8)
	v_mfma_f32_32x32x16_bf16 v[32:47], v[166:169], v[182:185], v[32:47]
	v_exp_f32_e32 v80, v112
	v_exp_f32_e32 v81, v113
	v_mfma_f32_32x32x16_bf16 v[32:47], v[12:15], v[178:181], v[32:47]
	v_exp_f32_e32 v82, v114
	v_exp_f32_e32 v83, v115
	v_mfma_f32_32x32x16_bf16 v[32:47], v[8:11], v[174:177], v[32:47]
	v_exp_f32_e32 v84, v116
	v_exp_f32_e32 v85, v117
	v_mfma_f32_32x32x16_bf16 v[32:47], v[4:7], v[170:173], v[32:47]
	v_exp_f32_e32 v86, v118
	v_exp_f32_e32 v87, v119
	s_waitcnt lgkmcnt(0)
	s_waitcnt vmcnt(0)
	s_barrier
	v_mfma_f32_32x32x16_bf16 v[16:31], v[166:169], v[198:201], v[16:31]
	v_exp_f32_e32 v88, v120
	v_exp_f32_e32 v89, v121
	v_mfma_f32_32x32x16_bf16 v[16:31], v[12:15], v[230:233], v[16:31]
	v_exp_f32_e32 v90, v122
	v_exp_f32_e32 v91, v123
	v_mfma_f32_32x32x16_bf16 v[16:31], v[8:11], v[234:237], v[16:31]
	v_exp_f32_e32 v92, v124
	v_exp_f32_e32 v93, v125
	v_mfma_f32_32x32x16_bf16 v[16:31], v[4:7], v[238:241], v[16:31]
	v_exp_f32_e32 v94, v126
	v_exp_f32_e32 v95, v127
	v_cmp_gt_f32_e32 vcc, 1.0, v225
	s_cbranch_vccnz .Lresc_odd_blk
.LBB0_1437:
	s_waitcnt vmcnt(0)
	s_add_i32 s54, s44, 1
	s_cmp_lg_u32 s44, 2
	s_cselect_b32 s67, s54, 0
	s_waitcnt vmcnt(0)
	s_lshl_b32 s66, s67, 14
	s_add_i32 s54, s81, s66
	v_lshl_add_u64 v[4:5], v[190:191], 0, s[52:53]
	s_mov_b32 m0, s54
	s_add_i32 s52, s71, s82
	global_load_lds_dwordx4 v[4:5], off
	v_lshl_add_u64 v[4:5], v[4:5], 0, s[14:15]
	s_add_i32 m0, s54, 0x2000
	s_add_i32 s52, s52, s27
	global_load_lds_dwordx4 v[4:5], off
	s_add_i32 m0, s52, 0xc000
	s_cmp_ge_u32 s45, s2
	s_cselect_b64 s[52:53], -1, 0
	s_cmp_lt_u32 s45, s2
	s_cselect_b32 s54, s45, s3
	s_lshl_b32 s54, s54, 6
	v_mad_u64_u32 v[4:5], s[54:55], s54, v209, v[192:193]
	v_lshl_add_u64 v[4:5], v[4:5], 0, s[10:11]
	global_load_lds_dwordx4 v[4:5], off
	v_cvt_f32_u32_e32 v1, s65
	s_mul_i32 s54, s44, 0x2100
	s_add_i32 s54, s54, 0
	v_add_u32_e32 v166, s54, v220
	v_sub_f32_e32 v196, v1, v161
	v_add_u32_e32 v167, s54, v217
	v_fma_f32 v1, v210, v196, -v221
	ds_read_b128 v[4:7], v166 offset:49152
	ds_read_b128 v[8:11], v167 offset:49152
	v_cvt_pk_bf16_f32 v2, v1, v3
	v_lshlrev_b32_e32 v2, 16, v2
	v_sub_f32_e32 v1, v1, v2
	v_cvt_pk_bf16_f32 v12, v1, v3
	v_lshlrev_b32_e32 v12, 16, v12
	v_sub_f32_e32 v1, v1, v12
	v_cvt_pk_bf16_f32 v12, v2, v12
	v_cvt_pk_bf16_f32 v1, v1, v3
	s_nop 0
	v_cndmask_b32_e64 v2, 0, v1, s[4:5]
	v_cndmask_b32_e64 v1, 0, v12, s[4:5]
	s_nop 1
	v_mfma_f32_32x32x16_bf16 v[128:143], v[248:251], v[0:3], 0
	v_add_f32_e32 v226, v96, v97
	v_add_f32_e32 v226, v98, v226
	v_add_f32_e32 v226, v99, v226
	v_add_f32_e32 v226, v100, v226
	s_nop 0
	v_mfma_f32_32x32x16_bf16 v[112:127], v[252:255], v[0:3], 0
	v_add_f32_e32 v1, v101, v226
	v_add_f32_e32 v1, v102, v1
	s_waitcnt lgkmcnt(0)
	v_mfma_f32_32x32x16_bf16 v[128:143], v[8:11], v[156:159], v[128:143]
	v_add_f32_e32 v1, v103, v1
	v_add_f32_e32 v1, v104, v1
	v_add_f32_e32 v1, v105, v1
	v_add_f32_e32 v1, v106, v1
	v_add_f32_e32 v1, v107, v1
	v_add_f32_e32 v1, v108, v1
	v_add_f32_e32 v1, v109, v1
	v_mfma_f32_32x32x16_bf16 v[112:127], v[4:7], v[156:159], v[112:127]
	ds_read_b128 v[4:7], v166 offset:51264
	ds_read_b128 v[8:11], v167 offset:51264
	v_add_f32_e32 v1, v110, v1
	v_add_f32_e32 v1, v111, v1
	v_add_f32_e32 v1, v80, v1
	v_add_f32_e32 v1, v81, v1
	v_add_f32_e32 v1, v82, v1
	v_add_f32_e32 v1, v83, v1
	s_waitcnt lgkmcnt(0)
	v_mfma_f32_32x32x16_bf16 v[128:143], v[8:11], v[152:155], v[128:143]
	v_add_f32_e32 v1, v84, v1
	v_add_f32_e32 v1, v85, v1
	v_add_f32_e32 v1, v86, v1
	v_add_f32_e32 v1, v87, v1
	v_add_f32_e32 v1, v88, v1
	v_add_f32_e32 v1, v89, v1
	v_add_f32_e32 v1, v90, v1
	v_mfma_f32_32x32x16_bf16 v[112:127], v[4:7], v[152:155], v[112:127]
	ds_read_b128 v[4:7], v166 offset:53376
	ds_read_b128 v[8:11], v167 offset:53376
	v_add_f32_e32 v1, v91, v1
	v_add_f32_e32 v1, v92, v1
	v_add_f32_e32 v1, v93, v1
	v_add_f32_e32 v1, v94, v1
	v_add_f32_e32 v1, v95, v1
	v_mov_b32_e32 v2, v1
	s_waitcnt lgkmcnt(0)
	v_mfma_f32_32x32x16_bf16 v[128:143], v[8:11], v[148:151], v[128:143]
	v_permlane32_swap_b32_e32 v1, v2
	v_mfma_f32_32x32x16_bf16 v[112:127], v[4:7], v[148:151], v[112:127]
	ds_read_b128 v[4:7], v166 offset:55488
	ds_read_b128 v[8:11], v167 offset:55488
	v_cvt_pk_bf16_f32 v166, v96, v97
	v_cvt_pk_bf16_f32 v167, v98, v99
	v_cvt_pk_bf16_f32 v168, v100, v101
	v_cvt_pk_bf16_f32 v169, v102, v103
	v_cvt_pk_bf16_f32 v12, v104, v105
	v_cvt_pk_bf16_f32 v13, v106, v107
	s_waitcnt lgkmcnt(0)
	v_mfma_f32_32x32x16_bf16 v[128:143], v[8:11], v[144:147], v[128:143]
	v_cvt_pk_bf16_f32 v14, v108, v109
	v_cvt_pk_bf16_f32 v15, v110, v111
	v_cvt_pk_bf16_f32 v8, v80, v81
	v_cvt_pk_bf16_f32 v9, v82, v83
	v_cvt_pk_bf16_f32 v10, v84, v85
	v_cvt_pk_bf16_f32 v11, v86, v87
	v_mfma_f32_32x32x16_bf16 v[112:127], v[4:7], v[144:147], v[112:127]
	v_cvt_pk_bf16_f32 v4, v88, v89
	v_cvt_pk_bf16_f32 v5, v90, v91
	v_cvt_pk_bf16_f32 v6, v92, v93
	v_cvt_pk_bf16_f32 v7, v94, v95
	v_lshl_add_u32 v162, s69, 14, v215
	ds_read_b64_tr_b16 v[182:183], v162 offset:0
	ds_read_b64_tr_b16 v[184:185], v162 offset:0x800
	ds_read_b64_tr_b16 v[178:179], v162 offset:0x1000
	ds_read_b64_tr_b16 v[180:181], v162 offset:0x1800
	s_add_i32 s54, s64, s45
	ds_read_b64_tr_b16 v[174:175], v162 offset:0x2000
	s_cmp_eq_u32 s54, 4
	ds_read_b64_tr_b16 v[176:177], v162 offset:0x2800
	s_cselect_b64 s[54:55], -1, 0
	ds_read_b64_tr_b16 v[170:171], v162 offset:0x3000
	v_cndmask_b32_e64 v80, 0, 1, s[54:55]
	ds_read_b64_tr_b16 v[172:173], v162 offset:0x3800
	s_add_i32 s98, s70, 2
	s_cmp_le_i32 s98, s31
	s_cbranch_scc0 .Lold_even
	v_max3_f32 v245, v128, v129, v130
	v_max3_f32 v246, v112, v113, v114
	v_max3_f32 v245, v245, v131, v132
	v_max3_f32 v246, v246, v115, v116
	v_max3_f32 v245, v245, v133, v134
	v_max3_f32 v246, v246, v117, v118
	v_max3_f32 v245, v245, v135, v136
	v_max3_f32 v246, v246, v119, v120
	v_max3_f32 v245, v245, v137, v138
	v_max3_f32 v246, v246, v121, v122
	v_max3_f32 v245, v245, v139, v140
	v_max3_f32 v246, v246, v123, v124
	v_max3_f32 v245, v245, v141, v142
	v_max3_f32 v246, v246, v125, v126
	v_max_f32_e32 v245, v245, v143
	v_max_f32_e32 v246, v246, v127
	v_max_f32_e32 v245, v245, v246
	v_mov_b32_e32 v246, v245
	s_nop 1
	v_permlane32_swap_b32_e32 v245, v246
	v_max_f32_e32 v245, v245, v246
	v_cmp_ge_f32_e32 vcc, s68, v245
	s_cmp_eq_u64 vcc, exec
	v_mov_b32_e32 v196, 1.0
	s_cbranch_scc0 .Lf_even_resc
.Lf_even_exp:
	ds_read_b64_tr_b16 v[198:199], v162 offset:0x200
	ds_read_b64_tr_b16 v[200:201], v162 offset:0xa00
	ds_read_b64_tr_b16 v[230:231], v162 offset:0x1200
	ds_read_b64_tr_b16 v[232:233], v162 offset:0x1a00
	ds_read_b64_tr_b16 v[234:235], v162 offset:0x2200
	ds_read_b64_tr_b16 v[236:237], v162 offset:0x2a00
	ds_read_b64_tr_b16 v[238:239], v162 offset:0x3200
	ds_read_b64_tr_b16 v[240:241], v162 offset:0x3a00
	s_waitcnt lgkmcnt(8)
	v_mfma_f32_32x32x16_bf16 v[64:79], v[166:169], v[182:185], v[64:79]
	v_exp_f32_e32 v96, v128
	v_exp_f32_e32 v97, v129
	v_mfma_f32_32x32x16_bf16 v[64:79], v[12:15], v[178:181], v[64:79]
	v_exp_f32_e32 v98, v130
	v_exp_f32_e32 v99, v131
	v_mfma_f32_32x32x16_bf16 v[64:79], v[8:11], v[174:177], v[64:79]
	v_exp_f32_e32 v100, v132
	v_exp_f32_e32 v101, v133
	v_mfma_f32_32x32x16_bf16 v[64:79], v[4:7], v[170:173], v[64:79]
	v_exp_f32_e32 v102, v134
	v_exp_f32_e32 v103, v135
	ds_read_b64_tr_b16 v[182:183], v162 offset:0x400
	ds_read_b64_tr_b16 v[184:185], v162 offset:0xc00
	ds_read_b64_tr_b16 v[178:179], v162 offset:0x1400
	ds_read_b64_tr_b16 v[180:181], v162 offset:0x1c00
	ds_read_b64_tr_b16 v[174:175], v162 offset:0x2400
	ds_read_b64_tr_b16 v[176:177], v162 offset:0x2c00
	ds_read_b64_tr_b16 v[170:171], v162 offset:0x3400
	ds_read_b64_tr_b16 v[172:173], v162 offset:0x3c00
	s_waitcnt lgkmcnt(8)
	v_mfma_f32_32x32x16_bf16 v[48:63], v[166:169], v[198:201], v[48:63]
	v_exp_f32_e32 v104, v136
	v_exp_f32_e32 v105, v137
	v_mfma_f32_32x32x16_bf16 v[48:63], v[12:15], v[230:233], v[48:63]
	v_exp_f32_e32 v106, v138
	v_exp_f32_e32 v107, v139
	v_mfma_f32_32x32x16_bf16 v[48:63], v[8:11], v[234:237], v[48:63]
	v_exp_f32_e32 v108, v140
	v_exp_f32_e32 v109, v141
	v_mfma_f32_32x32x16_bf16 v[48:63], v[4:7], v[238:241], v[48:63]
	v_exp_f32_e32 v110, v142
	v_exp_f32_e32 v111, v143
	ds_read_b64_tr_b16 v[198:199], v162 offset:0x600
	ds_read_b64_tr_b16 v[200:201], v162 offset:0xe00
	ds_read_b64_tr_b16 v[230:231], v162 offset:0x1600
	ds_read_b64_tr_b16 v[232:233], v162 offset:0x1e00
	ds_read_b64_tr_b16 v[234:235], v162 offset:0x2600
	ds_read_b64_tr_b16 v[236:237], v162 offset:0x2e00
	ds_read_b64_tr_b16 v[238:239], v162 offset:0x3600
	ds_read_b64_tr_b16 v[240:241], v162 offset:0x3e00
	s_waitcnt lgkmcnt(8)
	v_mfma_f32_32x32x16_bf16 v[32:47], v[166:169], v[182:185], v[32:47]
	v_exp_f32_e32 v80, v112
	v_exp_f32_e32 v81, v113
	v_mfma_f32_32x32x16_bf16 v[32:47], v[12:15], v[178:181], v[32:47]
	v_exp_f32_e32 v82, v114
	v_exp_f32_e32 v83, v115
	v_mfma_f32_32x32x16_bf16 v[32:47], v[8:11], v[174:177], v[32:47]
	v_exp_f32_e32 v84, v116
	v_exp_f32_e32 v85, v117
	v_mfma_f32_32x32x16_bf16 v[32:47], v[4:7], v[170:173], v[32:47]
	v_exp_f32_e32 v86, v118
	v_exp_f32_e32 v87, v119
	s_waitcnt lgkmcnt(0)
	s_waitcnt vmcnt(0)
	s_barrier
	v_mfma_f32_32x32x16_bf16 v[16:31], v[166:169], v[198:201], v[16:31]
	v_exp_f32_e32 v88, v120
	v_exp_f32_e32 v89, v121
	v_mfma_f32_32x32x16_bf16 v[16:31], v[12:15], v[230:233], v[16:31]
	v_exp_f32_e32 v90, v122
	v_exp_f32_e32 v91, v123
	v_mfma_f32_32x32x16_bf16 v[16:31], v[8:11], v[234:237], v[16:31]
	v_exp_f32_e32 v92, v124
	v_exp_f32_e32 v93, v125
	v_mfma_f32_32x32x16_bf16 v[16:31], v[4:7], v[238:241], v[16:31]
	v_exp_f32_e32 v94, v126
	v_exp_f32_e32 v95, v127
	v_cmp_gt_f32_e32 vcc, 1.0, v196
	s_cbranch_vccnz .Lresc_even_blk
.LBB0_1452:
	v_add_f32_e32 v4, v223, v224
	s_waitcnt vmcnt(0)
	s_add_i32 s54, s67, 1
	v_fmac_f32_e32 v4, v222, v214
	v_add_f32_e32 v214, v1, v2
	s_cmp_lg_u32 s67, 2
	v_fmac_f32_e32 v214, v4, v225
	s_cselect_b32 s55, s54, 0
	s_add_i32 s45, s45, 2
	s_addk_i32 s65, 0x80
	v_lshl_add_u64 v[194:195], v[194:195], 0, s[16:17]
	s_and_b64 vcc, exec, s[52:53]
	s_waitcnt vmcnt(0)
	s_cbranch_vccnz .LBB0_1458
	s_mov_b32 s54, s44
	s_mov_b32 s69, s67
	s_mov_b32 s44, s55
	v_mov_b32_e32 v222, v196
	s_branch .LBB0_1422
.Lold_odd:
	s_cmp_le_i32 s70, s31
	v_readfirstlane_b32 s54, v2
	s_cselect_b32 s66, s54, 2
	s_cmp_gt_i32 s66, 1
	s_cbranch_scc0 .LBB0_1425
	s_mov_b64 s[54:55], -1
	v_mov_b32_e32 v197, 0xf149f2ca
	s_cbranch_execz .LBB0_1426
	v_mov_b32_e32 v142, 0xf149f2ca
	v_mov_b32_e32 v141, 0xf149f2ca
	v_mov_b32_e32 v140, 0xf149f2ca
	v_mov_b32_e32 v139, 0xf149f2ca
	v_mov_b32_e32 v138, 0xf149f2ca
	v_mov_b32_e32 v137, 0xf149f2ca
	v_mov_b32_e32 v136, 0xf149f2ca
	v_mov_b32_e32 v135, 0xf149f2ca
	v_mov_b32_e32 v134, 0xf149f2ca
	v_mov_b32_e32 v133, 0xf149f2ca
	v_mov_b32_e32 v132, 0xf149f2ca
	v_mov_b32_e32 v131, 0xf149f2ca
	v_mov_b32_e32 v130, 0xf149f2ca
	v_mov_b32_e32 v129, 0xf149f2ca
	v_mov_b32_e32 v128, 0xf149f2ca
	v_mov_b32_e32 v127, 0xf149f2ca
	v_mov_b32_e32 v126, 0xf149f2ca
	v_mov_b32_e32 v125, 0xf149f2ca
	v_mov_b32_e32 v124, 0xf149f2ca
	v_mov_b32_e32 v123, 0xf149f2ca
	v_mov_b32_e32 v122, 0xf149f2ca
	v_mov_b32_e32 v121, 0xf149f2ca
	v_mov_b32_e32 v120, 0xf149f2ca
	v_mov_b32_e32 v119, 0xf149f2ca
	v_mov_b32_e32 v118, 0xf149f2ca
	v_mov_b32_e32 v117, 0xf149f2ca
	v_mov_b32_e32 v116, 0xf149f2ca
	v_mov_b32_e32 v115, 0xf149f2ca
	v_mov_b32_e32 v114, 0xf149f2ca
	v_mov_b32_e32 v113, 0xf149f2ca
	v_mov_b32_e32 v112, 0xf149f2ca
	s_and_b64 vcc, exec, s[54:55]
	s_cbranch_vccnz .LBB0_1429
	s_branch .LBB0_1430

.LBB0_1433:
	ds_read_b64_tr_b16 v[114:115], v1 offset:0x200
	ds_read_b64_tr_b16 v[116:117], v1 offset:0xa00
	ds_read_b64_tr_b16 v[118:119], v1 offset:0x1200
	ds_read_b64_tr_b16 v[120:121], v1 offset:0x1a00
	ds_read_b64_tr_b16 v[122:123], v1 offset:0x2200
	ds_read_b64_tr_b16 v[124:125], v1 offset:0x2a00
	ds_read_b64_tr_b16 v[130:131], v1 offset:0x3200
	ds_read_b64_tr_b16 v[132:133], v1 offset:0x3a00
	s_waitcnt lgkmcnt(8)
	v_exp_f32_e32 v96, v128
	v_mfma_f32_32x32x16_bf16 v[64:79], v[166:169], v[182:185], v[64:79]
	v_exp_f32_e32 v80, v112
	v_mfma_f32_32x32x16_bf16 v[64:79], v[12:15], v[178:181], v[64:79]
	v_exp_f32_e32 v97, v97
	v_exp_f32_e32 v81, v81
	v_mfma_f32_32x32x16_bf16 v[64:79], v[8:11], v[174:177], v[64:79]
	v_exp_f32_e32 v98, v98
	v_exp_f32_e32 v82, v82
	v_mfma_f32_32x32x16_bf16 v[64:79], v[4:7], v[170:173], v[64:79]
	v_exp_f32_e32 v99, v99
	v_exp_f32_e32 v83, v83
	ds_read_b64_tr_b16 v[126:127], v1 offset:0x400
	ds_read_b64_tr_b16 v[128:129], v1 offset:0xc00
	ds_read_b64_tr_b16 v[134:135], v1 offset:0x1400
	ds_read_b64_tr_b16 v[136:137], v1 offset:0x1c00
	ds_read_b64_tr_b16 v[138:139], v1 offset:0x2400
	ds_read_b64_tr_b16 v[140:141], v1 offset:0x2c00
	ds_read_b64_tr_b16 v[170:171], v1 offset:0x3400
	ds_read_b64_tr_b16 v[172:173], v1 offset:0x3c00
	s_waitcnt lgkmcnt(8)
	s_nop 0
	v_exp_f32_e32 v100, v100
	v_mfma_f32_32x32x16_bf16 v[48:63], v[166:169], v[114:117], v[48:63]
	v_exp_f32_e32 v84, v84
	v_mfma_f32_32x32x16_bf16 v[48:63], v[12:15], v[118:121], v[48:63]
	v_exp_f32_e32 v101, v101
	v_exp_f32_e32 v85, v85
	v_mfma_f32_32x32x16_bf16 v[48:63], v[8:11], v[122:125], v[48:63]
	v_exp_f32_e32 v102, v102
	v_exp_f32_e32 v86, v86
	v_mfma_f32_32x32x16_bf16 v[48:63], v[4:7], v[130:133], v[48:63]
	v_exp_f32_e32 v103, v103
	v_exp_f32_e32 v87, v87
	ds_read_b64_tr_b16 v[112:113], v1 offset:0x600
	ds_read_b64_tr_b16 v[114:115], v1 offset:0xe00
	ds_read_b64_tr_b16 v[116:117], v1 offset:0x1600
	ds_read_b64_tr_b16 v[118:119], v1 offset:0x1e00
	ds_read_b64_tr_b16 v[120:121], v1 offset:0x2600
	ds_read_b64_tr_b16 v[122:123], v1 offset:0x2e00
	ds_read_b64_tr_b16 v[130:131], v1 offset:0x3600
	ds_read_b64_tr_b16 v[132:133], v1 offset:0x3e00
	s_waitcnt lgkmcnt(8)
	s_nop 0
	v_exp_f32_e32 v104, v104
	v_mfma_f32_32x32x16_bf16 v[32:47], v[166:169], v[126:129], v[32:47]
	v_exp_f32_e32 v88, v88
	v_mfma_f32_32x32x16_bf16 v[32:47], v[12:15], v[134:137], v[32:47]
	v_exp_f32_e32 v105, v105
	v_exp_f32_e32 v89, v89
	v_mfma_f32_32x32x16_bf16 v[32:47], v[8:11], v[138:141], v[32:47]
	v_exp_f32_e32 v106, v106
	v_exp_f32_e32 v90, v90
	v_mfma_f32_32x32x16_bf16 v[32:47], v[4:7], v[170:173], v[32:47]
	v_exp_f32_e32 v107, v107
	v_exp_f32_e32 v91, v91
	s_waitcnt lgkmcnt(0)
	s_waitcnt vmcnt(0)
	s_barrier
	s_nop 0
	v_exp_f32_e32 v108, v108
	v_mfma_f32_32x32x16_bf16 v[16:31], v[166:169], v[112:115], v[16:31]
	v_exp_f32_e32 v92, v92
	v_mfma_f32_32x32x16_bf16 v[16:31], v[12:15], v[116:119], v[16:31]
	v_exp_f32_e32 v109, v109
	v_exp_f32_e32 v93, v93
	v_mfma_f32_32x32x16_bf16 v[16:31], v[8:11], v[120:123], v[16:31]
	v_exp_f32_e32 v110, v110
	v_exp_f32_e32 v94, v94
	v_mfma_f32_32x32x16_bf16 v[16:31], v[4:7], v[130:133], v[16:31]
	v_exp_f32_e32 v111, v111
	v_exp_f32_e32 v95, v95
	v_cmp_gt_f32_e32 vcc, 1.0, v225
	s_cbranch_vccz .LBB0_1437

.LBB0_1448:
	ds_read_b64_tr_b16 v[114:115], v162 offset:0x200
	ds_read_b64_tr_b16 v[116:117], v162 offset:0xa00
	ds_read_b64_tr_b16 v[118:119], v162 offset:0x1200
	ds_read_b64_tr_b16 v[120:121], v162 offset:0x1a00
	ds_read_b64_tr_b16 v[122:123], v162 offset:0x2200
	ds_read_b64_tr_b16 v[124:125], v162 offset:0x2a00
	ds_read_b64_tr_b16 v[130:131], v162 offset:0x3200
	ds_read_b64_tr_b16 v[132:133], v162 offset:0x3a00
	s_waitcnt lgkmcnt(8)
	v_exp_f32_e32 v96, v128
	v_mfma_f32_32x32x16_bf16 v[64:79], v[166:169], v[182:185], v[64:79]
	v_exp_f32_e32 v80, v112
	v_mfma_f32_32x32x16_bf16 v[64:79], v[12:15], v[178:181], v[64:79]
	v_exp_f32_e32 v97, v97
	v_exp_f32_e32 v81, v81
	v_mfma_f32_32x32x16_bf16 v[64:79], v[8:11], v[174:177], v[64:79]
	v_exp_f32_e32 v98, v98
	v_exp_f32_e32 v82, v82
	v_mfma_f32_32x32x16_bf16 v[64:79], v[4:7], v[170:173], v[64:79]
	v_exp_f32_e32 v99, v99
	v_exp_f32_e32 v83, v83
	ds_read_b64_tr_b16 v[126:127], v162 offset:0x400
	ds_read_b64_tr_b16 v[128:129], v162 offset:0xc00
	ds_read_b64_tr_b16 v[134:135], v162 offset:0x1400
	ds_read_b64_tr_b16 v[136:137], v162 offset:0x1c00
	ds_read_b64_tr_b16 v[138:139], v162 offset:0x2400
	ds_read_b64_tr_b16 v[140:141], v162 offset:0x2c00
	ds_read_b64_tr_b16 v[170:171], v162 offset:0x3400
	ds_read_b64_tr_b16 v[172:173], v162 offset:0x3c00
	s_waitcnt lgkmcnt(8)
	s_nop 0
	v_exp_f32_e32 v100, v100
	v_mfma_f32_32x32x16_bf16 v[48:63], v[166:169], v[114:117], v[48:63]
	v_exp_f32_e32 v84, v84
	v_mfma_f32_32x32x16_bf16 v[48:63], v[12:15], v[118:121], v[48:63]
	v_exp_f32_e32 v101, v101
	v_exp_f32_e32 v85, v85
	v_mfma_f32_32x32x16_bf16 v[48:63], v[8:11], v[122:125], v[48:63]
	v_exp_f32_e32 v102, v102
	v_exp_f32_e32 v86, v86
	v_mfma_f32_32x32x16_bf16 v[48:63], v[4:7], v[130:133], v[48:63]
	v_exp_f32_e32 v103, v103
	v_exp_f32_e32 v87, v87
	ds_read_b64_tr_b16 v[112:113], v162 offset:0x600
	ds_read_b64_tr_b16 v[114:115], v162 offset:0xe00
	ds_read_b64_tr_b16 v[116:117], v162 offset:0x1600
	ds_read_b64_tr_b16 v[118:119], v162 offset:0x1e00
	ds_read_b64_tr_b16 v[120:121], v162 offset:0x2600
	ds_read_b64_tr_b16 v[122:123], v162 offset:0x2e00
	ds_read_b64_tr_b16 v[130:131], v162 offset:0x3600
	ds_read_b64_tr_b16 v[132:133], v162 offset:0x3e00
	s_waitcnt lgkmcnt(8)
	s_nop 0
	v_exp_f32_e32 v104, v104
	v_mfma_f32_32x32x16_bf16 v[32:47], v[166:169], v[126:129], v[32:47]
	v_exp_f32_e32 v88, v88
	v_mfma_f32_32x32x16_bf16 v[32:47], v[12:15], v[134:137], v[32:47]
	v_exp_f32_e32 v105, v105
	v_exp_f32_e32 v89, v89
	v_mfma_f32_32x32x16_bf16 v[32:47], v[8:11], v[138:141], v[32:47]
	v_exp_f32_e32 v106, v106
	v_exp_f32_e32 v90, v90
	v_mfma_f32_32x32x16_bf16 v[32:47], v[4:7], v[170:173], v[32:47]
	v_exp_f32_e32 v107, v107
	v_exp_f32_e32 v91, v91
	s_waitcnt lgkmcnt(0)
	s_waitcnt vmcnt(0)
	s_barrier
	s_nop 0
	v_exp_f32_e32 v108, v108
	v_mfma_f32_32x32x16_bf16 v[16:31], v[166:169], v[112:115], v[16:31]
	v_exp_f32_e32 v92, v92
	v_mfma_f32_32x32x16_bf16 v[16:31], v[12:15], v[116:119], v[16:31]
	v_exp_f32_e32 v109, v109
	v_exp_f32_e32 v93, v93
	v_mfma_f32_32x32x16_bf16 v[16:31], v[8:11], v[120:123], v[16:31]
	v_exp_f32_e32 v110, v110
	v_exp_f32_e32 v94, v94
	v_mfma_f32_32x32x16_bf16 v[16:31], v[4:7], v[130:133], v[16:31]
	v_exp_f32_e32 v111, v111
	v_exp_f32_e32 v95, v95
	v_cmp_gt_f32_e32 vcc, 1.0, v196
	s_cbranch_vccz .LBB0_1452
